# XCD-local barriers also around the HGRN2 mixer: hgrn items of batch b run on XCD b (REC_IN -> pass1 -> pass2 -> out-proj stay inside one XCD): 26 of 31 barriers local
# speedup vs baseline: 1.0402x; 1.0007x over previous
; DI int obid() { int b = blockIdx.x; asm volatile("" : "+s"(b)); return b; }
; DI int ogrid() { int g = gridDim.x; asm volatile("" : "+s"(g)); return g; }
; DI int otid_w(int gw) { return (gw << 6) | olane(); }
; template <bool FULL>
; DI void hgrn_pass(const Params& p, const int j, char* lds) {
;     ...
;     const int tid512 = otid_w(p.wave), grp = tid512 >> 8, tid = tid512 & 255, lane = tid & 63, w = tid >> 6, l31 = lane & 31, hh = lane >> 5;
;     constexpr int LQ = 136, LV = 40, LO = 132;
;     float* tot = (float*)(lds + grp * 57344);
;     float* dvec = tot + 256;
;     float* Bc = dvec + 128;
;     float* Ot = Bc;
;     bf16_t* Qh = (bf16_t*)(Bc + 32 * LO);
;     bf16_t* Kt = Qh + 32 * LQ;
;     bf16_t* KhT = Kt + 32 * LQ;
;     bf16_t* VTs = KhT + 128 * LV;
;     const int kk = tid & 127, half = tid >> 7;
;     for (int item0 = obid() * 2; item0 < 512; item0 += ogrid() * 2) {
;         const int item = item0 + grp, bh = item >> 3, seg = item & 7, b = bh >> 3, h = bh & 7;
.LBB0_114:
	v_writelane_b32 v255, s86, 10
	s_movk_i32 s10, 0x1000
	s_and_b64 vcc, exec, s[4:5]
	v_writelane_b32 v255, s87, 11
	s_cbranch_vccz .LBB0_319
	v_readlane_b32 s4, v255, 6
	s_bitcmp1_b32 s4, 0
	v_readlane_b32 s5, v255, 7
	s_cselect_b64 s[6:7], -1, 0
	s_add_u32 s86, s68, 0x8681000
	s_addc_u32 s87, s69, 0
	s_mov_b64 s[4:5], -1
	s_and_b64 vcc, exec, s[6:7]
	s_cbranch_vccz .LBB0_195
	s_and_b32 s4, s2, 7
	s_lshl_b32 s4, s4, 5
	s_lshr_b32 s98, s2, 3
	s_or_b32 s4, s4, s98
	s_waitcnt vmcnt(0)
	v_mbcnt_lo_u32_b32 v0, -1, 0
	v_mbcnt_hi_u32_b32 v0, -1, v0
	s_cmpk_gt_i32 s4, 0xff
	s_cbranch_scc1 .LBB0_127
	v_mov_b32_e32 v2, s71
	s_lshl_b32 s6, s4, 1
	s_movk_i32 s4, 0x7f
	v_or_b32_e32 v5, s71, v0
	v_bitop3_b32 v11, v0, s74, v2 bitop3:0xc8
	v_bitop3_b32 v2, v0, s4, v2 bitop3:0xc8
	v_ashrrev_i32_e32 v91, 8, v5
	v_lshrrev_b32_e32 v3, 3, v5
	v_lshlrev_b32_e32 v32, 2, v2
	v_lshlrev_b32_e32 v14, 4, v0
	v_mul_i32_i24_e32 v1, 0xe000, v91
	v_and_b32_e32 v90, 16, v3
	v_lshl_add_u64 v[2:3], s[68:69], 0, v[32:33]
	s_mov_b64 s[4:5], 0x10681000
	v_and_b32_e32 v6, 48, v14
	v_mov_b32_e32 v7, v33
	v_and_b32_e32 v10, 31, v0
	v_bfe_u32 v13, v5, 6, 2
	v_lshl_add_u64 v[92:93], v[2:3], 0, s[4:5]
	v_lshl_add_u64 v[8:9], s[68:69], 0, v[6:7]
	s_mov_b64 s[4:5], 0xe681000
	v_or_b32_e32 v16, v1, v6
	v_lshrrev_b32_e32 v6, 1, v0
	v_lshl_add_u64 v[94:95], v[8:9], 0, s[4:5]
	v_and_or_b32 v107, v6, 16, v1
	v_lshl_or_b32 v6, v13, 5, v10
	s_movk_i32 s4, 0x50
	v_and_b32_e32 v12, 63, v0
	v_mad_u32_u24 v109, v6, s4, v107
	v_lshlrev_b32_e32 v6, 13, v13
	v_lshl_add_u64 v[6:7], s[68:69], 0, v[6:7]
	v_lshlrev_b32_e32 v8, 5, v12
	v_mov_b32_e32 v9, v33
	v_lshlrev_b32_e32 v4, 3, v0
	v_lshl_add_u64 v[6:7], v[6:7], 0, v[8:9]
	s_mov_b64 s[4:5], 0x14681000
	v_and_b32_e32 v4, 0x78, v4
	v_and_b32_e32 v15, 7, v0
	v_lshl_add_u64 v[96:97], v[6:7], 0, s[4:5]
	s_mov_b64 s[4:5], 0x15681000
	v_lshl_add_u64 v[98:99], v[2:3], 0, s[4:5]
	v_or_b32_e32 v2, 0x100, v11
	v_or_b32_e32 v6, v4, v15
	v_bfe_u32 v130, v5, 4, 4
	v_lshrrev_b32_e32 v132, 4, v2
	v_mul_u32_u24_e32 v117, 0x50, v6
	v_bitop3_b32 v6, v4, 1, v15 bitop3:0x36
	v_lshl_or_b32 v101, v11, 2, v1
	v_or_b32_e32 v103, v1, v32
	v_lshl_or_b32 v105, v4, 2, v1
	v_lshl_or_b32 v115, v130, 1, v1
	v_mul_u32_u24_e32 v119, 0x50, v6
	v_bitop3_b32 v6, v4, 2, v15 bitop3:0x36
	v_lshl_or_b32 v133, v132, 1, v1
	v_bfe_u32 v1, v0, 3, 2
	v_cmp_gt_u32_e32 vcc, s78, v11
	v_mul_u32_u24_e32 v121, 0x50, v6
	v_bitop3_b32 v6, v4, 3, v15 bitop3:0x36
	v_bitop3_b32 v9, v1, v0, 31 bitop3:0x78
	v_or_b32_e32 v11, 32, v10
	v_bitop3_b32 v1, v1, v10, 64 bitop3:0x1e
	v_mul_u32_u24_e32 v123, 0x50, v6
	v_bitop3_b32 v6, v4, 4, v15 bitop3:0x36
	v_lshrrev_b32_e32 v11, 3, v11
	v_mul_u32_u24_e32 v12, 0x50, v1
	v_or_b32_e32 v1, 0x60, v10
	v_mul_u32_u24_e32 v125, 0x50, v6
	v_bitop3_b32 v6, v4, 5, v15 bitop3:0x36
	v_bitop3_b32 v11, v11, v10, 32 bitop3:0x1e
	v_lshrrev_b32_e32 v10, 3, v1
	v_mul_u32_u24_e32 v127, 0x50, v6
	v_bitop3_b32 v6, v4, 6, v15 bitop3:0x36
	v_bitop3_b32 v1, v10, v1, 7 bitop3:0x6c
	v_mul_u32_u24_e32 v129, 0x50, v6
	v_bitop3_b32 v6, v4, 7, v0 bitop3:0x34
	v_mul_u32_u24_e32 v10, 0x50, v1
	v_and_b32_e32 v0, 3, v0
	v_mov_b32_e32 v1, 0xe681040
	v_lshl_or_b32 v134, v0, 4, v1
	v_mul_u32_u24_e32 v0, 0x1800, v132
	v_and_b32_e32 v13, 0xf0, v14
	v_mul_hi_u32_u24_e32 v1, 0x1800, v132
	v_or_b32_e32 v0, v0, v13
	s_mov_b64 s[4:5], 0x86b1800
	v_lshl_add_u64 v[136:137], v[0:1], 0, s[4:5]
	v_mul_u32_u24_e32 v0, 0x1800, v130
	v_bfe_u32 v111, v5, 2, 6
	v_lshrrev_b32_e32 v113, 2, v2
	v_mul_hi_u32_u24_e32 v1, 0x1800, v130
	v_or_b32_e32 v0, v0, v13
	v_mul_u32_u24_e32 v2, 0x210, v90
	v_mul_u32_u24_e32 v3, 0x210, v130
	v_mul_u32_u24_e32 v131, 0x50, v6
	v_mul_u32_u24_e32 v6, 0x210, v132
	v_mul_u32_u24_e32 v7, 0x50, v111
	v_mul_u32_u24_e32 v8, 0x50, v113
	v_mul_u32_u24_e32 v9, 0x50, v9
	v_mul_u32_u24_e32 v11, 0x50, v11
	v_lshl_add_u64 v[138:139], v[0:1], 0, s[4:5]
	v_lshlrev_b32_e32 v0, 9, v5
	s_mov_b32 s4, 0x10000
	v_or_b32_e32 v100, 1, v90
	v_or_b32_e32 v102, 2, v90
	v_or_b32_e32 v104, 3, v90
	v_or_b32_e32 v106, 4, v90
	v_or_b32_e32 v108, 5, v90
	v_or_b32_e32 v110, 6, v90
	v_or_b32_e32 v112, 7, v90
	v_or_b32_e32 v114, 8, v90
	v_or_b32_e32 v116, 9, v90
	v_or_b32_e32 v118, 10, v90
	v_or_b32_e32 v120, 11, v90
	v_or_b32_e32 v122, 12, v90
	v_or_b32_e32 v124, 13, v90
	v_or_b32_e32 v126, 14, v90
	v_or_b32_e32 v128, 15, v90
	v_mov_b32_e32 v135, v33
	v_and_or_b32 v140, v0, s4, v32
	v_lshlrev_b32_e32 v142, 1, v4
	v_add_u32_e32 v141, v103, v2
	v_add_u32_e32 v156, v105, v3
	v_add_u32_e32 v157, v105, v6
	v_add_u32_e32 v158, v16, v7
	v_add_u32_e32 v159, v16, v8
	v_add_u32_e32 v160, v107, v9
	v_add_u32_e32 v161, v107, v11
	v_add_u32_e32 v162, v107, v12
	v_add_u32_e32 v163, v107, v10
	s_branch .LBB0_119

; DI int olane() { int l; asm volatile("v_mbcnt_lo_u32_b32 %0, -1, 0\n\tv_mbcnt_hi_u32_b32 %0, -1, %0" : "=v"(l)); return l; }
; DI unsigned xb_ld(unsigned* p)              { return __hip_atomic_load(p, __ATOMIC_RELAXED, __HIP_MEMORY_SCOPE_AGENT); }
; DI unsigned xb_add(unsigned* p, unsigned v) { return __hip_atomic_fetch_add(p, v, __ATOMIC_RELAXED, __HIP_MEMORY_SCOPE_AGENT); }
; #define XB_SPIN(cond, bar) do { unsigned _sp = 0; while (cond) { __builtin_amdgcn_s_sleep(1); \
;     if ((++_sp & 255u) == 0u) { if (xb_ld(&(bar)[XB_TMO])) break; if (_sp > XB_SPIN_CAP) { atomicAdd(&(bar)[XB_TMO], 1u); break; } } } } while (0)
; DI void xcd_barrier(const XcdBarrier& b, const int gw) {
;     asm volatile("s_waitcnt vmcnt(0)" ::: "memory");
;     __syncthreads();
;     if (gw == 0 && olane() == 0) {
;         unsigned* bar = b.bar;
;         __builtin_amdgcn_s_waitcnt(0);
;         unsigned nloc = b.st[0], nx = b.st[1];
;         if (nloc == 0u) { xcd_barrier_complete(bar, b.x, nloc, nx); b.st[0] = nloc; b.st[1] = nx; }
;         const unsigned old = xb_add(&bar[XB_XSUB(b.x)], 1u);
;         const unsigned gen = old / nloc;
;         if (old + 1u == (gen + 1u) * nloc) {
;             __builtin_amdgcn_fence(__ATOMIC_RELEASE, "agent");
;             asm volatile("s_waitcnt vmcnt(0)" ::: "memory");
;             const unsigned og = xb_add(&bar[XB_TOP], 1u);
;             const unsigned tg = og / nx;
;             if (og + 1u == (tg + 1u) * nx) xb_add(&bar[XB_TOPGEN], 1u);
;             else XB_SPIN(xb_ld(&bar[XB_TOPGEN]) == tg, bar);
;             __builtin_amdgcn_fence(__ATOMIC_ACQUIRE, "agent");
;             xb_add(&bar[XB_XGEN(b.x)], 1u);
;             asm volatile("s_waitcnt vmcnt(0)" ::: "memory");
;         } else {
;             XB_SPIN(xb_ld(&bar[XB_XGEN(b.x)]) == gen, bar);
;             __builtin_amdgcn_fence(__ATOMIC_ACQUIRE, "agent");
;             asm volatile("s_waitcnt vmcnt(0)" ::: "memory");
;         }
.LBB0_160:
	s_andn2_saveexec_b64 s[8:9], s[8:9]
	s_cbranch_execz .LBB0_180
	s_mov_b64 s[8:9], exec
	v_mov_b32_e32 v1, 0x20048
	ds_read_b32 v1, v1
	s_waitcnt lgkmcnt(0)
	v_readfirstlane_b32 s98, v1
	s_cmp_lg_u32 s98, 0
	s_cbranch_scc1 .LBB0_177
	buffer_wbl2 sc1
	s_waitcnt lgkmcnt(0)
	s_waitcnt vmcnt(0)
	v_mbcnt_lo_u32_b32 v1, s8, 0
	v_mbcnt_hi_u32_b32 v1, s9, v1
	v_cmp_eq_u32_e32 vcc, 0, v1
	s_and_saveexec_b64 s[10:11], vcc
	s_cbranch_execz .LBB0_163
	s_bcnt1_i32_b64 s8, s[8:9]
	v_mov_b32_e32 v2, s8
	v_readlane_b32 s8, v254, 50
	v_readlane_b32 s9, v254, 51
	s_nop 4
	global_atomic_add v2, v33, v2, s[8:9] sc0

; DI int obid() { int b = blockIdx.x; asm volatile("" : "+s"(b)); return b; }
; DI int ogrid() { int g = gridDim.x; asm volatile("" : "+s"(g)); return g; }
; DI int otid_w(int gw) { return (gw << 6) | olane(); }
; template <bool FULL>
; DI void hgrn_pass(const Params& p, const int j, char* lds) {
;     ...
;     const int tid512 = otid_w(p.wave), grp = tid512 >> 8, tid = tid512 & 255, lane = tid & 63, w = tid >> 6, l31 = lane & 31, hh = lane >> 5;
;     constexpr int LQ = 136, LV = 40, LO = 132;
;     float* tot = (float*)(lds + grp * 57344);
;     float* dvec = tot + 256;
;     float* Bc = dvec + 128;
;     float* Ot = Bc;
;     bf16_t* Qh = (bf16_t*)(Bc + 32 * LO);
;     bf16_t* Kt = Qh + 32 * LQ;
;     bf16_t* KhT = Kt + 32 * LQ;
;     bf16_t* VTs = KhT + 128 * LV;
;     const int kk = tid & 127, half = tid >> 7;
;     for (int item0 = obid() * 2; item0 < 512; item0 += ogrid() * 2) {
;         const int item = item0 + grp, bh = item >> 3, seg = item & 7, b = bh >> 3, h = bh & 7;
.LBB0_181:
	s_and_b32 s4, s2, 7
	s_lshl_b32 s4, s4, 5
	s_lshr_b32 s98, s2, 3
	s_or_b32 s4, s4, s98
	s_waitcnt lgkmcnt(0)
	s_barrier
	v_mbcnt_lo_u32_b32 v0, -1, 0
	v_mbcnt_hi_u32_b32 v0, -1, v0
	s_cmpk_gt_i32 s4, 0xff
	s_cbranch_scc1 .LBB0_194
	v_mov_b32_e32 v2, s71
	s_lshl_b32 s88, s4, 1
	s_movk_i32 s4, 0x7f
	v_bitop3_b32 v10, v0, s74, v2 bitop3:0xc8
	v_bitop3_b32 v2, v0, s4, v2 bitop3:0xc8
	v_readlane_b32 s4, v255, 10
	v_or_b32_e32 v1, s71, v0
	s_mov_b32 s6, s4
	v_readlane_b32 s5, v255, 11
	v_writelane_b32 v255, s6, 10
	v_lshrrev_b32_e32 v3, 3, v1
	v_lshlrev_b32_e32 v32, 2, v2
	v_writelane_b32 v255, s7, 11
	v_and_b32_e32 v132, 16, v3
	v_lshl_add_u64 v[2:3], s[68:69], 0, v[32:33]
	s_mov_b64 s[6:7], 0x10681000
	v_ashrrev_i32_e32 v133, 8, v1
	v_lshl_add_u64 v[134:135], v[2:3], 0, s[6:7]
	v_lshlrev_b32_e32 v2, 3, v0
	v_lshlrev_b32_e32 v3, 4, v0
	v_mul_i32_i24_e32 v8, 0xe000, v133
	v_bfe_u32 v13, v0, 5, 1
	v_and_b32_e32 v2, 0x78, v2
	v_and_b32_e32 v4, 48, v3
	v_mov_b32_e32 v5, v33
	v_and_b32_e32 v9, 31, v0
	v_lshlrev_b32_e32 v15, 2, v13
	v_lshl_add_u64 v[6:7], s[68:69], 0, v[4:5]
	s_mov_b64 s[6:7], 0xe681000
	v_lshl_or_b32 v145, v2, 2, v8
	v_lshlrev_b32_e32 v5, 1, v2
	v_lshl_or_b32 v11, v9, 2, v8
	v_lshl_add_u64 v[136:137], v[6:7], 0, s[6:7]
	v_sub_u32_e32 v7, v145, v5
	v_or_b32_e32 v16, v8, v4
	v_mul_u32_u24_e32 v4, 0x10c, v9
	v_lshlrev_b32_e32 v5, 4, v13
	v_or_b32_e32 v19, 3, v15
	v_bfe_u32 v14, v1, 6, 2
	v_add3_u32 v149, v11, v4, v5
	v_mul_u32_u24_e32 v4, 0x110, v9
	s_mov_b32 s6, 0xe000
	v_cmp_gt_u32_e64 s[10:11], v19, v9
	v_or_b32_e32 v19, 8, v15
	v_mad_i32_i24 v17, v133, s6, v4
	v_lshl_or_b32 v4, v14, 5, v9
	v_cmp_gt_u32_e64 s[12:13], v19, v9
	v_or_b32_e32 v19, 9, v15
	v_mul_u32_u24_e32 v4, 0x50, v4
	v_cmp_gt_u32_e64 s[14:15], v19, v9
	v_or_b32_e32 v19, 10, v15
	s_mov_b32 s5, s89
	v_lshlrev_b32_e32 v147, 3, v13
	v_mad_i32_i24 v4, v133, s6, v4
	v_cmp_gt_u32_e64 s[16:17], v19, v9
	v_or_b32_e32 v19, 11, v15
	s_lshl_b64 s[4:5], s[4:5], 9
	v_bfe_u32 v138, v1, 3, 5
	v_or_b32_e32 v151, v4, v147
	v_lshlrev_b32_e32 v4, 6, v0
	v_cmp_gt_u32_e64 s[18:19], v19, v9
	v_or_b32_e32 v19, 16, v15
	s_add_u32 s4, s56, s4
	v_or_b32_e32 v153, v8, v5
	v_mul_u32_u24_e32 v5, 0x210, v138
	v_and_b32_e32 v4, 0x1c0, v4
	v_cmp_gt_u32_e64 s[20:21], v19, v9
	v_or_b32_e32 v19, 17, v15
	s_addc_u32 s5, s57, s5
	v_and_b32_e32 v6, 7, v0
	v_add3_u32 v155, v8, v5, v4
	v_mov_b32_e32 v5, v33
	v_cmp_gt_u32_e64 s[22:23], v19, v9
	v_or_b32_e32 v19, 18, v15
	v_lshl_or_b32 v139, v10, 2, v8
	v_cmp_gt_u32_e64 s[38:39], s78, v10
	v_lshl_add_u64 v[140:141], s[4:5], 0, v[4:5]
	v_or_b32_e32 v4, 0x100, v10
	v_or_b32_e32 v10, v2, v6
	v_cmp_gt_u32_e64 s[24:25], v19, v9
	v_or_b32_e32 v19, 19, v15
	v_mul_u32_u24_e32 v169, 0x50, v10
	v_bitop3_b32 v10, v2, 1, v6 bitop3:0x36
	v_cmp_gt_u32_e64 s[26:27], v19, v9
	v_or_b32_e32 v19, 24, v15
	v_mul_u32_u24_e32 v184, 0x50, v10
	v_bitop3_b32 v10, v2, 2, v6 bitop3:0x36
	v_cmp_gt_u32_e64 s[28:29], v19, v9
	v_or_b32_e32 v19, 25, v15
	v_mul_u32_u24_e32 v185, 0x50, v10
	v_bitop3_b32 v10, v2, 3, v6 bitop3:0x36
	v_cmp_gt_u32_e64 s[4:5], v15, v9
	v_cmp_lt_u32_e64 s[6:7], v15, v9
	v_or_b32_e32 v18, 2, v15
	v_cmp_gt_u32_e64 s[30:31], v19, v9
	v_or_b32_e32 v19, 26, v15
	v_or_b32_e32 v15, 27, v15
	v_or_b32_e32 v20, 32, v9
	v_mul_u32_u24_e32 v186, 0x50, v10
	v_bitop3_b32 v10, v2, 4, v6 bitop3:0x36
	v_cmp_gt_u32_e64 s[36:37], v15, v9
	v_bfe_u32 v15, v0, 3, 2
	v_lshrrev_b32_e32 v20, 3, v20
	v_and_b32_e32 v12, 63, v0
	v_mul_u32_u24_e32 v187, 0x50, v10
	v_bitop3_b32 v10, v2, 5, v6 bitop3:0x36
	v_cmp_gt_u32_e64 s[8:9], v18, v9
	v_cmp_gt_u32_e64 s[34:35], v19, v9
	v_bitop3_b32 v19, v15, v0, 31 bitop3:0x78
	v_bitop3_b32 v20, v20, v9, 32 bitop3:0x1e
	v_bitop3_b32 v15, v15, v9, 64 bitop3:0x1e
	v_or_b32_e32 v9, 0x60, v9
	v_mul_u32_u24_e32 v188, 0x50, v10
	v_bitop3_b32 v10, v2, 6, v6 bitop3:0x36
	v_lshrrev_b32_e32 v21, 3, v9
	v_lshlrev_b32_e32 v12, 5, v12
	v_lshrrev_b32_e32 v154, 4, v4
	v_mul_u32_u24_e32 v189, 0x50, v10
	v_bitop3_b32 v10, v2, 7, v0 bitop3:0x34
	v_bitop3_b32 v9, v21, v9, 7 bitop3:0x6c
	v_lshrrev_b32_e32 v21, 1, v0
	v_lshl_or_b32 v158, v14, 13, v12
	v_and_b32_e32 v0, 3, v0
	v_mov_b32_e32 v12, 0xe681040
	v_bfe_u32 v152, v1, 4, 4
	v_lshl_or_b32 v160, v0, 4, v12
	v_mul_u32_u24_e32 v0, 0x1800, v154
	v_and_b32_e32 v3, 0xf0, v3
	v_or_b32_e32 v162, v0, v3
	v_mul_u32_u24_e32 v0, 0x1800, v152
	v_or_b32_e32 v143, v8, v32
	v_lshl_or_b32 v11, v14, 7, v11
	v_bfe_u32 v157, v1, 2, 6
	v_lshrrev_b32_e32 v159, 2, v4
	v_lshl_or_b32 v167, v152, 1, v8
	v_mul_u32_u24_e32 v190, 0x50, v10
	v_mul_u32_u24_e32 v10, 0x88, v152
	v_lshl_or_b32 v192, v154, 1, v8
	v_mul_u32_u24_e32 v8, 0x88, v154
	v_mul_u32_u24_e32 v13, 0x840, v13
	v_or_b32_e32 v164, v0, v3
	v_lshlrev_b32_e32 v0, 9, v1
	s_mov_b32 s64, 0x10000
	v_mul_u32_u24_e32 v4, 0x210, v132
	v_mul_u32_u24_e32 v5, 0x210, v152
	v_lshl_add_u32 v191, v10, 1, v7
	v_mul_u32_u24_e32 v10, 0x210, v154
	v_lshl_add_u32 v194, v8, 1, v7
	v_mul_u32_u24_e32 v7, 0x50, v157
	v_mul_u32_u24_e32 v8, 0x50, v159
	v_mul_u32_u24_e32 v19, 0x50, v19
	v_mul_u32_u24_e32 v20, 0x50, v20
	v_mul_u32_u24_e32 v15, 0x50, v15
	v_mul_u32_u24_e32 v9, 0x50, v9
	v_mul_u32_u24_e32 v18, 0x210, v18
	v_and_or_b32 v166, v0, s64, v32
	v_add_u32_e32 v0, v11, v13
	v_or_b32_e32 v142, 11, v132
	v_or_b32_e32 v144, 12, v132
	v_or_b32_e32 v146, 13, v132
	v_or_b32_e32 v148, 14, v132
	v_or_b32_e32 v150, 15, v132
	v_and_b32_e32 v156, 16, v21
	v_mov_b32_e32 v161, v33
	v_mul_hi_u32_u24_e32 v163, 0x1800, v154
	v_mul_hi_u32_u24_e32 v165, 0x1800, v152
	v_lshlrev_b32_e32 v168, 5, v6
	v_lshlrev_b32_e32 v170, 1, v2
	v_add_u32_e32 v195, v143, v4
	v_add_u32_e32 v200, v145, v5
	v_add_u32_e32 v204, v145, v10
	v_add_u32_e32 v205, v16, v7
	v_add_u32_e32 v206, v16, v8
	v_add_u32_e32 v207, v17, v147
	v_add_u32_e32 v208, v153, v19
	v_add_u32_e32 v209, v153, v20
	v_add_u32_e32 v210, v153, v15
	v_add_u32_e32 v211, v153, v9
	v_add_u32_e32 v212, v11, v18
	v_add_u32_e32 v213, 0x600, v0
	s_branch .LBB0_184

; DI unsigned xb_ld(unsigned* p)              { return __hip_atomic_load(p, __ATOMIC_RELAXED, __HIP_MEMORY_SCOPE_AGENT); }
; DI unsigned xb_add(unsigned* p, unsigned v) { return __hip_atomic_fetch_add(p, v, __ATOMIC_RELAXED, __HIP_MEMORY_SCOPE_AGENT); }
; #define XB_SPIN(cond, bar) do { unsigned _sp = 0; while (cond) { __builtin_amdgcn_s_sleep(1); \
;     if ((++_sp & 255u) == 0u) { if (xb_ld(&(bar)[XB_TMO])) break; if (_sp > XB_SPIN_CAP) { atomicAdd(&(bar)[XB_TMO], 1u); break; } } } } while (0)
; DI void xcd_barrier(const XcdBarrier& b, const int gw) {
;     ...
;         const unsigned old = xb_add(&bar[XB_XSUB(b.x)], 1u);
;         const unsigned gen = old / nloc;
;         if (old + 1u == (gen + 1u) * nloc) {
;             __builtin_amdgcn_fence(__ATOMIC_RELEASE, "agent");
;             asm volatile("s_waitcnt vmcnt(0)" ::: "memory");
;             const unsigned og = xb_add(&bar[XB_TOP], 1u);
;             const unsigned tg = og / nx;
;             if (og + 1u == (tg + 1u) * nx) xb_add(&bar[XB_TOPGEN], 1u);
;             else XB_SPIN(xb_ld(&bar[XB_TOPGEN]) == tg, bar);
;             __builtin_amdgcn_fence(__ATOMIC_ACQUIRE, "agent");
;             xb_add(&bar[XB_XGEN(b.x)], 1u);
.LBB0_528:
	s_andn2_saveexec_b64 s[8:9], s[8:9]
	s_cbranch_execz .LBB0_548
	s_mov_b64 s[8:9], exec
	s_add_i32 s98, s36, -1
	s_lshr_b32 s98, 0x1ffe7ff8, s98
	s_bitcmp1_b32 s98, 0
	s_cbranch_scc0 .Lxb_global
	v_mov_b32_e32 v1, 0x20048
	ds_read_b32 v1, v1
	s_waitcnt lgkmcnt(0)
	v_readfirstlane_b32 s98, v1
	s_cmp_lg_u32 s98, 0
	s_cbranch_scc1 .LBB0_545
